# accumulator zeroing at K-loop entry uses 64-bit moves (64 instead of 127 VALU per tile)
# speedup vs baseline: 1.0086x; 1.0006x over previous
.LBB0_149:
	v_mov_b32_e32 v129, 0
	s_andn2_b64 vcc, exec, s[4:5]
	s_waitcnt vmcnt(0)
	s_cbranch_vccnz .Lzt_0
	s_add_u32 s41, s6, 0x100
	s_addc_u32 s42, s7, 0
	s_add_u32 s6, s8, 0xc000
	v_mov_b32_e32 v2, 0
	s_addc_u32 s7, s9, 0
	s_mov_b32 s8, 0
	v_mov_b64_e32 v[4:5], 0
	v_mov_b64_e32 v[6:7], 0
	v_mov_b64_e32 v[8:9], 0
	v_mov_b64_e32 v[10:11], 0
	v_mov_b64_e32 v[12:13], 0
	v_mov_b64_e32 v[14:15], 0
	v_mov_b64_e32 v[16:17], 0
	v_mov_b64_e32 v[18:19], 0
	v_mov_b64_e32 v[20:21], 0
	v_mov_b64_e32 v[22:23], 0
	v_mov_b64_e32 v[24:25], 0
	v_mov_b64_e32 v[26:27], 0
	v_mov_b64_e32 v[28:29], 0
	v_mov_b64_e32 v[30:31], 0
	v_mov_b64_e32 v[32:33], 0
	v_mov_b64_e32 v[34:35], 0
	v_mov_b64_e32 v[36:37], 0
	v_mov_b64_e32 v[38:39], 0
	v_mov_b64_e32 v[40:41], 0
	v_mov_b64_e32 v[42:43], 0
	v_mov_b64_e32 v[44:45], 0
	v_mov_b64_e32 v[46:47], 0
	v_mov_b64_e32 v[48:49], 0
	v_mov_b64_e32 v[50:51], 0
	v_mov_b64_e32 v[52:53], 0
	v_mov_b64_e32 v[54:55], 0
	v_mov_b64_e32 v[56:57], 0
	v_mov_b64_e32 v[58:59], 0
	v_mov_b64_e32 v[60:61], 0
	v_mov_b64_e32 v[62:63], 0
	v_mov_b64_e32 v[64:65], 0
	v_mov_b64_e32 v[66:67], 0
	v_mov_b64_e32 v[68:69], 0
	v_mov_b64_e32 v[70:71], 0
	v_mov_b64_e32 v[72:73], 0
	v_mov_b64_e32 v[74:75], 0
	v_mov_b64_e32 v[76:77], 0
	v_mov_b64_e32 v[78:79], 0
	v_mov_b64_e32 v[80:81], 0
	v_mov_b64_e32 v[82:83], 0
	v_mov_b64_e32 v[84:85], 0
	v_mov_b64_e32 v[86:87], 0
	v_mov_b64_e32 v[88:89], 0
	v_mov_b64_e32 v[90:91], 0
	v_mov_b64_e32 v[92:93], 0
	v_mov_b64_e32 v[94:95], 0
	v_mov_b64_e32 v[96:97], 0
	v_mov_b64_e32 v[98:99], 0
	v_mov_b64_e32 v[100:101], 0
	v_mov_b64_e32 v[102:103], 0
	v_mov_b64_e32 v[104:105], 0
	v_mov_b64_e32 v[106:107], 0
	v_mov_b64_e32 v[108:109], 0
	v_mov_b64_e32 v[110:111], 0
	v_mov_b64_e32 v[112:113], 0
	v_mov_b64_e32 v[114:115], 0
	v_mov_b64_e32 v[116:117], 0
	v_mov_b64_e32 v[118:119], 0
	v_mov_b64_e32 v[120:121], 0
	v_mov_b64_e32 v[122:123], 0
	v_mov_b64_e32 v[124:125], 0
	v_mov_b64_e32 v[126:127], 0
	v_mov_b64_e32 v[128:129], 0
	v_mov_b32_e32 v3, 0

.LBB0_164:
	s_ashr_i32 s7, s6, 31
	s_lshl_b64 s[8:9], s[6:7], 19
	s_add_u32 s8, s64, s8
	s_addc_u32 s9, s65, s9
	s_ashr_i32 s5, s4, 31
	s_lshl_b64 s[10:11], s[4:5], 19
	s_add_u32 s10, s21, s10
	v_mov_b32_e32 v141, 0
	s_addc_u32 s11, s22, s11
	s_andn2_b64 vcc, exec, s[2:3]
	s_waitcnt vmcnt(0)
	s_cbranch_vccnz .Lzt_2
	v_mov_b64_e32 v[2:3], 0xb00
	v_cmp_lt_i64_e32 vcc, s[18:19], v[2:3]
	s_and_b64 s[18:19], vcc, exec
	s_cselect_b32 s5, s9, s15
	s_cselect_b32 s7, s8, s14
	s_cselect_b32 s43, s11, s17
	s_cselect_b32 s44, s10, s16
	s_add_u32 s14, s14, 0x40080
	s_addc_u32 s15, s15, 0
	s_add_u32 s45, s16, 0x100
	v_mov_b32_e32 v2, 0
	s_addc_u32 s46, s17, 0
	s_mov_b32 s16, 0
	v_mov_b64_e32 v[4:5], 0
	v_mov_b64_e32 v[6:7], 0
	v_mov_b64_e32 v[8:9], 0
	v_mov_b64_e32 v[10:11], 0
	v_mov_b64_e32 v[12:13], 0
	v_mov_b64_e32 v[14:15], 0
	v_mov_b64_e32 v[16:17], 0
	v_mov_b64_e32 v[18:19], 0
	v_mov_b64_e32 v[20:21], 0
	v_mov_b64_e32 v[22:23], 0
	v_mov_b64_e32 v[24:25], 0
	v_mov_b64_e32 v[26:27], 0
	v_mov_b64_e32 v[28:29], 0
	v_mov_b64_e32 v[30:31], 0
	v_mov_b64_e32 v[32:33], 0
	v_mov_b64_e32 v[34:35], 0
	v_mov_b64_e32 v[36:37], 0
	v_mov_b64_e32 v[38:39], 0
	v_mov_b64_e32 v[40:41], 0
	v_mov_b64_e32 v[42:43], 0
	v_mov_b64_e32 v[44:45], 0
	v_mov_b64_e32 v[46:47], 0
	v_mov_b64_e32 v[48:49], 0
	v_mov_b64_e32 v[50:51], 0
	v_mov_b64_e32 v[52:53], 0
	v_mov_b64_e32 v[54:55], 0
	v_mov_b64_e32 v[56:57], 0
	v_mov_b64_e32 v[58:59], 0
	v_mov_b64_e32 v[60:61], 0
	v_mov_b64_e32 v[62:63], 0
	v_mov_b64_e32 v[64:65], 0
	v_mov_b64_e32 v[66:67], 0
	v_mov_b64_e32 v[68:69], 0
	v_mov_b64_e32 v[70:71], 0
	v_mov_b64_e32 v[72:73], 0
	v_mov_b64_e32 v[74:75], 0
	v_mov_b64_e32 v[76:77], 0
	v_mov_b64_e32 v[78:79], 0
	v_mov_b64_e32 v[80:81], 0
	v_mov_b64_e32 v[90:91], 0
	v_mov_b64_e32 v[92:93], 0
	v_mov_b64_e32 v[94:95], 0
	v_mov_b64_e32 v[96:97], 0
	v_mov_b64_e32 v[106:107], 0
	v_mov_b64_e32 v[108:109], 0
	v_mov_b64_e32 v[110:111], 0
	v_mov_b64_e32 v[112:113], 0
	v_mov_b64_e32 v[114:115], 0
	v_mov_b64_e32 v[116:117], 0
	v_mov_b64_e32 v[118:119], 0
	v_mov_b64_e32 v[120:121], 0
	v_mov_b64_e32 v[122:123], 0
	v_mov_b64_e32 v[124:125], 0
	v_mov_b64_e32 v[126:127], 0
	v_mov_b64_e32 v[128:129], 0
	v_mov_b64_e32 v[130:131], 0
	v_mov_b64_e32 v[132:133], 0
	v_mov_b64_e32 v[134:135], 0
	v_mov_b64_e32 v[136:137], 0
	v_mov_b64_e32 v[138:139], 0
	v_mov_b64_e32 v[140:141], 0
	v_mov_b64_e32 v[142:143], 0
	v_mov_b64_e32 v[144:145], 0
	v_mov_b32_e32 v3, 0

.LBB0_189:
	s_ashr_i32 s9, s8, 31
	s_lshl_b64 s[10:11], s[8:9], 19
	s_add_u32 s10, s23, s10
	s_addc_u32 s11, s24, s11
	s_ashr_i32 s7, s6, 31
	s_lshl_b64 s[12:13], s[6:7], 19
	s_add_u32 s12, s25, s12
	v_mov_b32_e32 v145, 0
	v_cmp_lt_i64_e64 s[0:1], s[0:1], v[162:163]
	s_addc_u32 s13, s26, s13
	s_andn2_b64 vcc, exec, s[4:5]
	s_waitcnt vmcnt(0)
	s_waitcnt lgkmcnt(0)
	s_cbranch_vccnz .Lzt_4
	s_and_b64 s[0:1], s[0:1], exec
	s_cselect_b32 s7, s11, s21
	s_cselect_b32 s9, s10, s20
	s_cselect_b32 s47, s13, s19
	s_cselect_b32 s48, s12, s18
	s_add_u32 s49, s18, 0x100
	s_addc_u32 s50, s19, 0
	s_add_u32 s0, s20, 0x40080
	v_mov_b32_e32 v2, 0
	s_addc_u32 s1, s21, 0
	s_mov_b32 s18, 0
	v_mov_b64_e32 v[4:5], 0
	v_mov_b64_e32 v[6:7], 0
	v_mov_b64_e32 v[8:9], 0
	v_mov_b64_e32 v[10:11], 0
	v_mov_b64_e32 v[12:13], 0
	v_mov_b64_e32 v[14:15], 0
	v_mov_b64_e32 v[16:17], 0
	v_mov_b64_e32 v[18:19], 0
	v_mov_b64_e32 v[20:21], 0
	v_mov_b64_e32 v[22:23], 0
	v_mov_b64_e32 v[24:25], 0
	v_mov_b64_e32 v[26:27], 0
	v_mov_b64_e32 v[28:29], 0
	v_mov_b64_e32 v[30:31], 0
	v_mov_b64_e32 v[32:33], 0
	v_mov_b64_e32 v[34:35], 0
	v_mov_b64_e32 v[36:37], 0
	v_mov_b64_e32 v[38:39], 0
	v_mov_b64_e32 v[40:41], 0
	v_mov_b64_e32 v[42:43], 0
	v_mov_b64_e32 v[44:45], 0
	v_mov_b64_e32 v[46:47], 0
	v_mov_b64_e32 v[48:49], 0
	v_mov_b64_e32 v[50:51], 0
	v_mov_b64_e32 v[52:53], 0
	v_mov_b64_e32 v[54:55], 0
	v_mov_b64_e32 v[56:57], 0
	v_mov_b64_e32 v[58:59], 0
	v_mov_b64_e32 v[60:61], 0
	v_mov_b64_e32 v[62:63], 0
	v_mov_b64_e32 v[64:65], 0
	v_mov_b64_e32 v[66:67], 0
	v_mov_b64_e32 v[68:69], 0
	v_mov_b64_e32 v[70:71], 0
	v_mov_b64_e32 v[72:73], 0
	v_mov_b64_e32 v[74:75], 0
	v_mov_b64_e32 v[76:77], 0
	v_mov_b64_e32 v[78:79], 0
	v_mov_b64_e32 v[80:81], 0
	v_mov_b64_e32 v[82:83], 0
	v_mov_b64_e32 v[84:85], 0
	v_mov_b64_e32 v[86:87], 0
	v_mov_b64_e32 v[88:89], 0
	v_mov_b64_e32 v[94:95], 0
	v_mov_b64_e32 v[96:97], 0
	v_mov_b64_e32 v[98:99], 0
	v_mov_b64_e32 v[100:101], 0
	v_mov_b64_e32 v[106:107], 0
	v_mov_b64_e32 v[108:109], 0
	v_mov_b64_e32 v[114:115], 0
	v_mov_b64_e32 v[116:117], 0
	v_mov_b64_e32 v[118:119], 0
	v_mov_b64_e32 v[120:121], 0
	v_mov_b64_e32 v[126:127], 0
	v_mov_b64_e32 v[128:129], 0
	v_mov_b64_e32 v[130:131], 0
	v_mov_b64_e32 v[132:133], 0
	v_mov_b64_e32 v[134:135], 0
	v_mov_b64_e32 v[136:137], 0
	v_mov_b64_e32 v[138:139], 0
	v_mov_b64_e32 v[140:141], 0
	v_mov_b64_e32 v[142:143], 0
	v_mov_b64_e32 v[144:145], 0
	v_mov_b32_e32 v3, 0

.LBB0_425:
	v_mov_b32_e32 v133, v0
	v_lshl_add_u64 v[2:3], s[0:1], 0, v[132:133]
	v_mov_b32_e32 v137, v0
	v_lshl_add_u64 v[4:5], s[0:1], 0, v[136:137]
	v_mov_b32_e32 v131, v0
	s_add_i32 m0, s15, 0x18000
	v_lshl_add_u64 v[2:3], v[2:3], 0, s[84:85]
	v_lshl_add_u64 v[6:7], s[2:3], 0, v[130:131]
	v_mov_b32_e32 v135, v0
	s_and_b32 s13, s8, 3
	s_lshl_b32 s12, s6, 6
	s_waitcnt vmcnt(4)
	s_barrier
	global_load_lds_dwordx4 v[2:3], off
	v_lshl_add_u64 v[2:3], v[4:5], 0, s[84:85]
	s_add_i32 m0, s15, 0x1a000
	s_add_i32 s19, s15, 0x8000
	s_add_i32 s20, s15, 0xa000
	v_lshl_add_u64 v[8:9], s[2:3], 0, v[134:135]
	global_load_lds_dwordx4 v[2:3], off
	v_lshl_add_u64 v[2:3], v[6:7], 0, s[84:85]
	s_mov_b32 m0, s19
	s_add_u32 s8, s0, 0x10080
	global_load_lds_dwordx4 v[2:3], off
	v_lshl_add_u64 v[2:3], v[8:9], 0, s[84:85]
	s_mov_b32 m0, s20
	s_addc_u32 s9, s1, 0
	global_load_lds_dwordx4 v[2:3], off
	s_add_i32 m0, s15, 0x1c000
	v_lshl_add_u64 v[2:3], s[8:9], 0, v[132:133]
	global_load_lds_dwordx4 v[2:3], off
	v_lshl_add_u64 v[2:3], s[8:9], 0, v[136:137]
	s_add_i32 m0, s15, 0x1e000
	v_bfe_u32 v1, v170, 4, 2
	global_load_lds_dwordx4 v[2:3], off
	v_and_b32_e32 v158, 15, v170
	v_lshlrev_b32_e32 v11, 2, v170
	s_waitcnt vmcnt(6)
	v_lshlrev_b32_e32 v146, 4, v1
	v_lshlrev_b32_e32 v10, 6, v158
	v_and_b32_e32 v11, 32, v11
	v_mov_b32_e32 v129, 0
	v_bitop3_b32 v147, v146, v11, v10 bitop3:0x36
	s_cmp_lt_i32 s4, 64
	v_mov_b32_e32 v128, v129
	s_waitcnt vmcnt(0)
	v_mov_b32_e32 v127, v129
	v_mov_b32_e32 v126, v129
	v_mov_b32_e32 v125, v129
	v_mov_b32_e32 v124, v129
	v_mov_b32_e32 v123, v129
	v_mov_b32_e32 v122, v129
	v_mov_b32_e32 v113, v129
	v_mov_b32_e32 v112, v129
	v_mov_b32_e32 v111, v129
	v_mov_b32_e32 v110, v129
	v_mov_b32_e32 v109, v129
	v_mov_b32_e32 v108, v129
	v_mov_b32_e32 v107, v129
	v_mov_b32_e32 v106, v129
	v_mov_b32_e32 v97, v129
	v_mov_b32_e32 v96, v129
	v_mov_b32_e32 v95, v129
	v_mov_b32_e32 v94, v129
	v_mov_b32_e32 v93, v129
	v_mov_b32_e32 v92, v129
	v_mov_b32_e32 v91, v129
	v_mov_b32_e32 v90, v129
	v_mov_b32_e32 v81, v129
	v_mov_b32_e32 v80, v129
	v_mov_b32_e32 v79, v129
	v_mov_b32_e32 v78, v129
	v_mov_b32_e32 v77, v129
	v_mov_b32_e32 v76, v129
	v_mov_b32_e32 v75, v129
	v_mov_b32_e32 v74, v129
	v_mov_b32_e32 v121, v129
	v_mov_b32_e32 v120, v129
	v_mov_b32_e32 v119, v129
	v_mov_b32_e32 v118, v129
	v_mov_b32_e32 v117, v129
	v_mov_b32_e32 v116, v129
	v_mov_b32_e32 v115, v129
	v_mov_b32_e32 v114, v129
	v_mov_b32_e32 v105, v129
	v_mov_b32_e32 v104, v129
	v_mov_b32_e32 v103, v129
	v_mov_b32_e32 v102, v129
	v_mov_b32_e32 v101, v129
	v_mov_b32_e32 v100, v129
	v_mov_b32_e32 v99, v129
	v_mov_b32_e32 v98, v129
	v_mov_b32_e32 v89, v129
	v_mov_b32_e32 v88, v129
	v_mov_b32_e32 v87, v129
	v_mov_b32_e32 v86, v129
	v_mov_b32_e32 v85, v129
	v_mov_b32_e32 v84, v129
	v_mov_b32_e32 v83, v129
	v_mov_b32_e32 v82, v129
	v_mov_b32_e32 v73, v129
	v_mov_b32_e32 v72, v129
	v_mov_b32_e32 v71, v129
	v_mov_b32_e32 v70, v129
	v_mov_b32_e32 v69, v129
	v_mov_b32_e32 v68, v129
	v_mov_b32_e32 v67, v129
	v_mov_b32_e32 v66, v129
	v_mov_b32_e32 v65, v129
	v_mov_b32_e32 v64, v129
	v_mov_b32_e32 v63, v129
	v_mov_b32_e32 v62, v129
	v_mov_b32_e32 v61, v129
	v_mov_b32_e32 v60, v129
	v_mov_b32_e32 v59, v129
	v_mov_b32_e32 v58, v129
	v_mov_b32_e32 v49, v129
	v_mov_b32_e32 v48, v129
	v_mov_b32_e32 v47, v129
	v_mov_b32_e32 v46, v129
	v_mov_b32_e32 v45, v129
	v_mov_b32_e32 v44, v129
	v_mov_b32_e32 v43, v129
	v_mov_b32_e32 v42, v129
	v_mov_b32_e32 v33, v129
	v_mov_b32_e32 v32, v129
	v_mov_b32_e32 v31, v129
	v_mov_b32_e32 v30, v129
	v_mov_b32_e32 v29, v129
	v_mov_b32_e32 v28, v129
	v_mov_b32_e32 v27, v129
	v_mov_b32_e32 v26, v129
	v_mov_b32_e32 v17, v129
	v_mov_b32_e32 v16, v129
	v_mov_b32_e32 v15, v129
	v_mov_b32_e32 v14, v129
	v_mov_b32_e32 v13, v129
	v_mov_b32_e32 v12, v129
	v_mov_b32_e32 v11, v129
	v_mov_b32_e32 v10, v129
	v_mov_b32_e32 v57, v129
	v_mov_b32_e32 v56, v129
	v_mov_b32_e32 v55, v129
	v_mov_b32_e32 v54, v129
	v_mov_b32_e32 v53, v129
	v_mov_b32_e32 v52, v129
	v_mov_b32_e32 v51, v129
	v_mov_b32_e32 v50, v129
	v_mov_b32_e32 v41, v129
	v_mov_b32_e32 v40, v129
	v_mov_b32_e32 v39, v129
	v_mov_b32_e32 v38, v129
	v_mov_b32_e32 v37, v129
	v_mov_b32_e32 v36, v129
	v_mov_b32_e32 v35, v129
	v_mov_b32_e32 v34, v129
	v_mov_b32_e32 v25, v129
	v_mov_b32_e32 v24, v129
	v_mov_b32_e32 v23, v129
	v_mov_b32_e32 v22, v129
	v_mov_b32_e32 v21, v129
	v_mov_b32_e32 v20, v129
	v_mov_b32_e32 v19, v129
	v_mov_b32_e32 v18, v129
	v_mov_b32_e32 v9, v129
	v_mov_b32_e32 v8, v129
	v_mov_b32_e32 v7, v129
	v_mov_b32_e32 v6, v129
	v_mov_b32_e32 v5, v129
	v_mov_b32_e32 v4, v129
	v_mov_b32_e32 v3, v129
	v_mov_b32_e32 v2, v129
	s_barrier
	s_cbranch_scc1 .LBB0_428
	s_ashr_i32 s8, s4, 31
	s_lshr_b32 s8, s8, 26
	s_add_i32 s4, s4, s8
	v_or_b32_e32 v2, s12, v158
	s_ashr_i32 s21, s4, 6
	v_lshlrev_b32_e32 v3, 6, v2
	s_movk_i32 s4, 0x3c0
	v_lshlrev_b32_e32 v2, 2, v2
	v_and_or_b32 v3, v3, s4, v146
	s_lshl_b32 s4, s6, 13
	v_and_b32_e32 v2, 32, v2
	v_bitop3_b32 v4, v3, s4, v2 bitop3:0xde
	v_lshlrev_b32_e32 v2, 12, v138
	s_lshl_b32 s4, s5, 17
	v_and_b32_e32 v2, 0xffffe000, v2
	s_and_b32 s4, s4, 0x1f00000
	s_lshl_b32 s5, s7, 17
	s_add_i32 s22, s21, -2
	v_lshl_add_u32 v2, v139, 9, v2
	v_and_b32_e32 v3, 1, v138
	s_add_i32 s4, s4, s5
	v_lshl_or_b32 v2, v3, 6, v2
	s_add_u32 s4, s66, s4
	v_lshl_add_u32 v2, v140, 1, v2
	v_mov_b32_e32 v3, v0
	s_addc_u32 s5, s67, 0
	v_lshl_add_u64 v[138:139], s[4:5], 0, v[2:3]
	v_lshlrev_b32_e32 v2, 12, v141
	v_and_b32_e32 v2, 0xffffe000, v2
	v_lshl_add_u32 v2, v143, 9, v2
	v_and_b32_e32 v3, 1, v141
	v_lshl_or_b32 v2, v3, 6, v2
	v_lshl_add_u32 v2, v144, 1, v2
	v_mov_b32_e32 v3, v0
	v_lshl_add_u64 v[140:141], s[4:5], 0, v[2:3]
	v_mov_b32_e32 v2, 0
	v_lshl_or_b32 v142, s13, 12, v147
	s_mov_b32 s6, 0
	s_mov_b64 s[4:5], 0x1d410080
	v_add_u32_e32 v143, 0, v4
	v_mov_b64_e32 v[4:5], 0
	v_mov_b64_e32 v[6:7], 0
	v_mov_b64_e32 v[8:9], 0
	v_mov_b64_e32 v[10:11], 0
	v_mov_b64_e32 v[12:13], 0
	v_mov_b64_e32 v[14:15], 0
	v_mov_b64_e32 v[16:17], 0
	v_mov_b64_e32 v[18:19], 0
	v_mov_b64_e32 v[20:21], 0
	v_mov_b64_e32 v[22:23], 0
	v_mov_b64_e32 v[24:25], 0
	v_mov_b64_e32 v[26:27], 0
	v_mov_b64_e32 v[28:29], 0
	v_mov_b64_e32 v[30:31], 0
	v_mov_b64_e32 v[32:33], 0
	v_mov_b64_e32 v[34:35], 0
	v_mov_b64_e32 v[36:37], 0
	v_mov_b64_e32 v[38:39], 0
	v_mov_b64_e32 v[40:41], 0
	v_mov_b64_e32 v[42:43], 0
	v_mov_b64_e32 v[44:45], 0
	v_mov_b64_e32 v[46:47], 0
	v_mov_b64_e32 v[48:49], 0
	v_mov_b64_e32 v[50:51], 0
	v_mov_b64_e32 v[52:53], 0
	v_mov_b64_e32 v[54:55], 0
	v_mov_b64_e32 v[56:57], 0
	v_mov_b64_e32 v[58:59], 0
	v_mov_b64_e32 v[60:61], 0
	v_mov_b64_e32 v[62:63], 0
	v_mov_b64_e32 v[64:65], 0
	v_mov_b64_e32 v[66:67], 0
	v_mov_b64_e32 v[68:69], 0
	v_mov_b64_e32 v[70:71], 0
	v_mov_b64_e32 v[72:73], 0
	v_mov_b64_e32 v[74:75], 0
	v_mov_b64_e32 v[76:77], 0
	v_mov_b64_e32 v[78:79], 0
	v_mov_b64_e32 v[80:81], 0
	v_mov_b64_e32 v[82:83], 0
	v_mov_b64_e32 v[84:85], 0
	v_mov_b64_e32 v[86:87], 0
	v_mov_b64_e32 v[88:89], 0
	v_mov_b64_e32 v[90:91], 0
	v_mov_b64_e32 v[92:93], 0
	v_mov_b64_e32 v[94:95], 0
	v_mov_b64_e32 v[96:97], 0
	v_mov_b64_e32 v[98:99], 0
	v_mov_b64_e32 v[100:101], 0
	v_mov_b64_e32 v[102:103], 0
	v_mov_b64_e32 v[104:105], 0
	v_mov_b64_e32 v[106:107], 0
	v_mov_b64_e32 v[108:109], 0
	v_mov_b64_e32 v[110:111], 0
	v_mov_b64_e32 v[112:113], 0
	v_mov_b64_e32 v[114:115], 0
	v_mov_b64_e32 v[116:117], 0
	v_mov_b64_e32 v[118:119], 0
	v_mov_b64_e32 v[120:121], 0
	v_mov_b64_e32 v[122:123], 0
	v_mov_b64_e32 v[124:125], 0
	v_mov_b64_e32 v[126:127], 0
	v_mov_b64_e32 v[128:129], 0
	v_mov_b32_e32 v3, 0

.LBB0_437:
	v_mov_b32_e32 v133, v0
	v_lshl_add_u64 v[2:3], s[0:1], 0, v[132:133]
	v_mov_b32_e32 v137, v0
	v_lshl_add_u64 v[4:5], s[0:1], 0, v[136:137]
	v_mov_b32_e32 v131, v0
	s_add_i32 m0, s15, 0x18000
	v_lshl_add_u64 v[2:3], v[2:3], 0, s[84:85]
	v_lshl_add_u64 v[6:7], s[2:3], 0, v[130:131]
	v_mov_b32_e32 v135, v0
	s_and_b32 s13, s8, 3
	s_lshl_b32 s12, s6, 6
	s_waitcnt vmcnt(4)
	s_barrier
	global_load_lds_dwordx4 v[2:3], off
	v_lshl_add_u64 v[2:3], v[4:5], 0, s[84:85]
	s_add_i32 m0, s15, 0x1a000
	s_add_i32 s19, s15, 0x8000
	s_add_i32 s20, s15, 0xa000
	v_lshl_add_u64 v[8:9], s[2:3], 0, v[134:135]
	global_load_lds_dwordx4 v[2:3], off
	v_lshl_add_u64 v[2:3], v[6:7], 0, s[84:85]
	s_mov_b32 m0, s19
	s_add_u32 s8, s0, 0x10080
	global_load_lds_dwordx4 v[2:3], off
	v_lshl_add_u64 v[2:3], v[8:9], 0, s[84:85]
	s_mov_b32 m0, s20
	s_addc_u32 s9, s1, 0
	global_load_lds_dwordx4 v[2:3], off
	s_add_i32 m0, s15, 0x1c000
	v_lshl_add_u64 v[2:3], s[8:9], 0, v[132:133]
	global_load_lds_dwordx4 v[2:3], off
	v_lshl_add_u64 v[2:3], s[8:9], 0, v[136:137]
	s_add_i32 m0, s15, 0x1e000
	v_bfe_u32 v1, v170, 4, 2
	global_load_lds_dwordx4 v[2:3], off
	v_and_b32_e32 v158, 15, v170
	v_lshlrev_b32_e32 v11, 2, v170
	s_waitcnt vmcnt(6)
	v_lshlrev_b32_e32 v146, 4, v1
	v_lshlrev_b32_e32 v10, 6, v158
	v_and_b32_e32 v11, 32, v11
	v_mov_b32_e32 v129, 0
	v_bitop3_b32 v147, v146, v11, v10 bitop3:0x36
	s_cmp_lt_i32 s4, 64
	v_mov_b32_e32 v128, v129
	s_waitcnt vmcnt(0)
	v_mov_b32_e32 v127, v129
	v_mov_b32_e32 v126, v129
	v_mov_b32_e32 v125, v129
	v_mov_b32_e32 v124, v129
	v_mov_b32_e32 v123, v129
	v_mov_b32_e32 v122, v129
	v_mov_b32_e32 v113, v129
	v_mov_b32_e32 v112, v129
	v_mov_b32_e32 v111, v129
	v_mov_b32_e32 v110, v129
	v_mov_b32_e32 v109, v129
	v_mov_b32_e32 v108, v129
	v_mov_b32_e32 v107, v129
	v_mov_b32_e32 v106, v129
	v_mov_b32_e32 v97, v129
	v_mov_b32_e32 v96, v129
	v_mov_b32_e32 v95, v129
	v_mov_b32_e32 v94, v129
	v_mov_b32_e32 v93, v129
	v_mov_b32_e32 v92, v129
	v_mov_b32_e32 v91, v129
	v_mov_b32_e32 v90, v129
	v_mov_b32_e32 v81, v129
	v_mov_b32_e32 v80, v129
	v_mov_b32_e32 v79, v129
	v_mov_b32_e32 v78, v129
	v_mov_b32_e32 v77, v129
	v_mov_b32_e32 v76, v129
	v_mov_b32_e32 v75, v129
	v_mov_b32_e32 v74, v129
	v_mov_b32_e32 v121, v129
	v_mov_b32_e32 v120, v129
	v_mov_b32_e32 v119, v129
	v_mov_b32_e32 v118, v129
	v_mov_b32_e32 v117, v129
	v_mov_b32_e32 v116, v129
	v_mov_b32_e32 v115, v129
	v_mov_b32_e32 v114, v129
	v_mov_b32_e32 v105, v129
	v_mov_b32_e32 v104, v129
	v_mov_b32_e32 v103, v129
	v_mov_b32_e32 v102, v129
	v_mov_b32_e32 v101, v129
	v_mov_b32_e32 v100, v129
	v_mov_b32_e32 v99, v129
	v_mov_b32_e32 v98, v129
	v_mov_b32_e32 v89, v129
	v_mov_b32_e32 v88, v129
	v_mov_b32_e32 v87, v129
	v_mov_b32_e32 v86, v129
	v_mov_b32_e32 v85, v129
	v_mov_b32_e32 v84, v129
	v_mov_b32_e32 v83, v129
	v_mov_b32_e32 v82, v129
	v_mov_b32_e32 v73, v129
	v_mov_b32_e32 v72, v129
	v_mov_b32_e32 v71, v129
	v_mov_b32_e32 v70, v129
	v_mov_b32_e32 v69, v129
	v_mov_b32_e32 v68, v129
	v_mov_b32_e32 v67, v129
	v_mov_b32_e32 v66, v129
	v_mov_b32_e32 v65, v129
	v_mov_b32_e32 v64, v129
	v_mov_b32_e32 v63, v129
	v_mov_b32_e32 v62, v129
	v_mov_b32_e32 v61, v129
	v_mov_b32_e32 v60, v129
	v_mov_b32_e32 v59, v129
	v_mov_b32_e32 v58, v129
	v_mov_b32_e32 v49, v129
	v_mov_b32_e32 v48, v129
	v_mov_b32_e32 v47, v129
	v_mov_b32_e32 v46, v129
	v_mov_b32_e32 v45, v129
	v_mov_b32_e32 v44, v129
	v_mov_b32_e32 v43, v129
	v_mov_b32_e32 v42, v129
	v_mov_b32_e32 v33, v129
	v_mov_b32_e32 v32, v129
	v_mov_b32_e32 v31, v129
	v_mov_b32_e32 v30, v129
	v_mov_b32_e32 v29, v129
	v_mov_b32_e32 v28, v129
	v_mov_b32_e32 v27, v129
	v_mov_b32_e32 v26, v129
	v_mov_b32_e32 v17, v129
	v_mov_b32_e32 v16, v129
	v_mov_b32_e32 v15, v129
	v_mov_b32_e32 v14, v129
	v_mov_b32_e32 v13, v129
	v_mov_b32_e32 v12, v129
	v_mov_b32_e32 v11, v129
	v_mov_b32_e32 v10, v129
	v_mov_b32_e32 v57, v129
	v_mov_b32_e32 v56, v129
	v_mov_b32_e32 v55, v129
	v_mov_b32_e32 v54, v129
	v_mov_b32_e32 v53, v129
	v_mov_b32_e32 v52, v129
	v_mov_b32_e32 v51, v129
	v_mov_b32_e32 v50, v129
	v_mov_b32_e32 v41, v129
	v_mov_b32_e32 v40, v129
	v_mov_b32_e32 v39, v129
	v_mov_b32_e32 v38, v129
	v_mov_b32_e32 v37, v129
	v_mov_b32_e32 v36, v129
	v_mov_b32_e32 v35, v129
	v_mov_b32_e32 v34, v129
	v_mov_b32_e32 v25, v129
	v_mov_b32_e32 v24, v129
	v_mov_b32_e32 v23, v129
	v_mov_b32_e32 v22, v129
	v_mov_b32_e32 v21, v129
	v_mov_b32_e32 v20, v129
	v_mov_b32_e32 v19, v129
	v_mov_b32_e32 v18, v129
	v_mov_b32_e32 v9, v129
	v_mov_b32_e32 v8, v129
	v_mov_b32_e32 v7, v129
	v_mov_b32_e32 v6, v129
	v_mov_b32_e32 v5, v129
	v_mov_b32_e32 v4, v129
	v_mov_b32_e32 v3, v129
	v_mov_b32_e32 v2, v129
	s_barrier
	s_cbranch_scc1 .LBB0_440
	s_ashr_i32 s8, s4, 31
	s_lshr_b32 s8, s8, 26
	s_add_i32 s4, s4, s8
	v_or_b32_e32 v2, s12, v158
	s_ashr_i32 s21, s4, 6
	v_lshlrev_b32_e32 v3, 6, v2
	s_movk_i32 s4, 0x3c0
	v_lshlrev_b32_e32 v2, 2, v2
	v_and_or_b32 v3, v3, s4, v146
	s_lshl_b32 s4, s6, 13
	v_and_b32_e32 v2, 32, v2
	v_bitop3_b32 v4, v3, s4, v2 bitop3:0xde
	v_lshlrev_b32_e32 v2, 12, v138
	s_lshl_b32 s4, s5, 17
	v_and_b32_e32 v2, 0xffffe000, v2
	s_and_b32 s4, s4, 0x1f00000
	s_lshl_b32 s5, s7, 17
	s_add_i32 s22, s21, -2
	v_lshl_add_u32 v2, v139, 9, v2
	v_and_b32_e32 v3, 1, v138
	s_add_i32 s4, s4, s5
	v_lshl_or_b32 v2, v3, 6, v2
	s_add_u32 s4, s66, s4
	v_lshl_add_u32 v2, v140, 1, v2
	v_mov_b32_e32 v3, v0
	s_addc_u32 s5, s67, 0
	v_lshl_add_u64 v[138:139], s[4:5], 0, v[2:3]
	v_lshlrev_b32_e32 v2, 12, v141
	v_and_b32_e32 v2, 0xffffe000, v2
	v_lshl_add_u32 v2, v143, 9, v2
	v_and_b32_e32 v3, 1, v141
	v_lshl_or_b32 v2, v3, 6, v2
	v_lshl_add_u32 v2, v144, 1, v2
	v_mov_b32_e32 v3, v0
	v_lshl_add_u64 v[140:141], s[4:5], 0, v[2:3]
	v_mov_b32_e32 v2, 0
	v_lshl_or_b32 v142, s13, 12, v147
	s_mov_b32 s6, 0
	s_mov_b64 s[4:5], 0x1d210080
	v_add_u32_e32 v143, 0, v4
	v_mov_b64_e32 v[4:5], 0
	v_mov_b64_e32 v[6:7], 0
	v_mov_b64_e32 v[8:9], 0
	v_mov_b64_e32 v[10:11], 0
	v_mov_b64_e32 v[12:13], 0
	v_mov_b64_e32 v[14:15], 0
	v_mov_b64_e32 v[16:17], 0
	v_mov_b64_e32 v[18:19], 0
	v_mov_b64_e32 v[20:21], 0
	v_mov_b64_e32 v[22:23], 0
	v_mov_b64_e32 v[24:25], 0
	v_mov_b64_e32 v[26:27], 0
	v_mov_b64_e32 v[28:29], 0
	v_mov_b64_e32 v[30:31], 0
	v_mov_b64_e32 v[32:33], 0
	v_mov_b64_e32 v[34:35], 0
	v_mov_b64_e32 v[36:37], 0
	v_mov_b64_e32 v[38:39], 0
	v_mov_b64_e32 v[40:41], 0
	v_mov_b64_e32 v[42:43], 0
	v_mov_b64_e32 v[44:45], 0
	v_mov_b64_e32 v[46:47], 0
	v_mov_b64_e32 v[48:49], 0
	v_mov_b64_e32 v[50:51], 0
	v_mov_b64_e32 v[52:53], 0
	v_mov_b64_e32 v[54:55], 0
	v_mov_b64_e32 v[56:57], 0
	v_mov_b64_e32 v[58:59], 0
	v_mov_b64_e32 v[60:61], 0
	v_mov_b64_e32 v[62:63], 0
	v_mov_b64_e32 v[64:65], 0
	v_mov_b64_e32 v[66:67], 0
	v_mov_b64_e32 v[68:69], 0
	v_mov_b64_e32 v[70:71], 0
	v_mov_b64_e32 v[72:73], 0
	v_mov_b64_e32 v[74:75], 0
	v_mov_b64_e32 v[76:77], 0
	v_mov_b64_e32 v[78:79], 0
	v_mov_b64_e32 v[80:81], 0
	v_mov_b64_e32 v[82:83], 0
	v_mov_b64_e32 v[84:85], 0
	v_mov_b64_e32 v[86:87], 0
	v_mov_b64_e32 v[88:89], 0
	v_mov_b64_e32 v[90:91], 0
	v_mov_b64_e32 v[92:93], 0
	v_mov_b64_e32 v[94:95], 0
	v_mov_b64_e32 v[96:97], 0
	v_mov_b64_e32 v[98:99], 0
	v_mov_b64_e32 v[100:101], 0
	v_mov_b64_e32 v[102:103], 0
	v_mov_b64_e32 v[104:105], 0
	v_mov_b64_e32 v[106:107], 0
	v_mov_b64_e32 v[108:109], 0
	v_mov_b64_e32 v[110:111], 0
	v_mov_b64_e32 v[112:113], 0
	v_mov_b64_e32 v[114:115], 0
	v_mov_b64_e32 v[116:117], 0
	v_mov_b64_e32 v[118:119], 0
	v_mov_b64_e32 v[120:121], 0
	v_mov_b64_e32 v[122:123], 0
	v_mov_b64_e32 v[124:125], 0
	v_mov_b64_e32 v[126:127], 0
	v_mov_b64_e32 v[128:129], 0
	v_mov_b32_e32 v3, 0

.LBB0_452:
	s_ashr_i32 s11, s10, 31
	s_lshl_b64 s[12:13], s[10:11], 19
	s_add_u32 s12, s64, s12
	s_addc_u32 s13, s65, s13
	s_ashr_i32 s9, s8, 31
	s_lshl_b64 s[14:15], s[8:9], 19
	s_add_u32 s14, s25, s14
	s_waitcnt vmcnt(0)
	v_mov_b32_e32 v121, 0
	s_addc_u32 s15, s26, s15
	s_andn2_b64 vcc, exec, s[6:7]
	s_cbranch_vccnz .Lzt_10
	v_mov_b64_e32 v[2:3], 0x280
	v_cmp_lt_i64_e32 vcc, s[22:23], v[2:3]
	s_and_b64 s[22:23], vcc, exec
	s_cselect_b32 s9, s13, s19
	s_cselect_b32 s11, s12, s18
	s_cselect_b32 s48, s15, s21
	s_cselect_b32 s49, s14, s20
	s_add_u32 s18, s18, 0x40080
	s_addc_u32 s19, s19, 0
	s_add_u32 s50, s20, 0x100
	v_mov_b32_e32 v6, 0
	s_addc_u32 s51, s21, 0
	s_mov_b32 s20, 0
	v_mov_b64_e32 v[2:3], 0
	v_mov_b64_e32 v[4:5], 0
	v_mov_b64_e32 v[8:9], 0
	v_mov_b64_e32 v[10:11], 0
	v_mov_b64_e32 v[12:13], 0
	v_mov_b64_e32 v[14:15], 0
	v_mov_b64_e32 v[16:17], 0
	v_mov_b64_e32 v[18:19], 0
	v_mov_b64_e32 v[20:21], 0
	v_mov_b64_e32 v[22:23], 0
	v_mov_b64_e32 v[24:25], 0
	v_mov_b64_e32 v[26:27], 0
	v_mov_b64_e32 v[28:29], 0
	v_mov_b64_e32 v[30:31], 0
	v_mov_b64_e32 v[32:33], 0
	v_mov_b64_e32 v[34:35], 0
	v_mov_b64_e32 v[36:37], 0
	v_mov_b64_e32 v[38:39], 0
	v_mov_b64_e32 v[40:41], 0
	v_mov_b64_e32 v[42:43], 0
	v_mov_b64_e32 v[44:45], 0
	v_mov_b64_e32 v[46:47], 0
	v_mov_b64_e32 v[48:49], 0
	v_mov_b64_e32 v[50:51], 0
	v_mov_b64_e32 v[52:53], 0
	v_mov_b64_e32 v[54:55], 0
	v_mov_b64_e32 v[56:57], 0
	v_mov_b64_e32 v[58:59], 0
	v_mov_b64_e32 v[60:61], 0
	v_mov_b64_e32 v[62:63], 0
	v_mov_b64_e32 v[64:65], 0
	v_mov_b64_e32 v[66:67], 0
	v_mov_b64_e32 v[68:69], 0
	v_mov_b64_e32 v[70:71], 0
	v_mov_b64_e32 v[72:73], 0
	v_mov_b64_e32 v[74:75], 0
	v_mov_b64_e32 v[76:77], 0
	v_mov_b64_e32 v[78:79], 0
	v_mov_b64_e32 v[80:81], 0
	v_mov_b64_e32 v[82:83], 0
	v_mov_b64_e32 v[84:85], 0
	v_mov_b64_e32 v[86:87], 0
	v_mov_b64_e32 v[88:89], 0
	v_mov_b64_e32 v[90:91], 0
	v_mov_b64_e32 v[92:93], 0
	v_mov_b64_e32 v[94:95], 0
	v_mov_b64_e32 v[96:97], 0
	v_mov_b64_e32 v[98:99], 0
	v_mov_b64_e32 v[100:101], 0
	v_mov_b64_e32 v[102:103], 0
	v_mov_b64_e32 v[104:105], 0
	v_mov_b64_e32 v[106:107], 0
	v_mov_b64_e32 v[108:109], 0
	v_mov_b64_e32 v[110:111], 0
	v_mov_b64_e32 v[112:113], 0
	v_mov_b64_e32 v[114:115], 0
	v_mov_b64_e32 v[116:117], 0
	v_mov_b64_e32 v[118:119], 0
	v_mov_b64_e32 v[120:121], 0
	v_mov_b64_e32 v[122:123], 0
	v_mov_b64_e32 v[124:125], 0
	v_mov_b64_e32 v[126:127], 0
	v_mov_b64_e32 v[128:129], 0
	v_mov_b32_e32 v7, 0

.LBB0_498:
	v_mov_b32_e32 v145, 0
	s_andn2_b64 vcc, exec, s[6:7]
	s_waitcnt lgkmcnt(0)
	s_cbranch_vccnz .Lzt_12
	s_add_u32 s45, s8, 0x100
	s_addc_u32 s46, s9, 0
	s_add_u32 s8, s10, 0xc000
	v_mov_b32_e32 v2, 0
	s_addc_u32 s9, s11, 0
	s_mov_b32 s10, 0
	v_mov_b64_e32 v[4:5], 0
	v_mov_b64_e32 v[6:7], 0
	v_mov_b64_e32 v[8:9], 0
	v_mov_b64_e32 v[10:11], 0
	v_mov_b64_e32 v[12:13], 0
	v_mov_b64_e32 v[14:15], 0
	v_mov_b64_e32 v[16:17], 0
	v_mov_b64_e32 v[18:19], 0
	v_mov_b64_e32 v[20:21], 0
	v_mov_b64_e32 v[22:23], 0
	v_mov_b64_e32 v[24:25], 0
	v_mov_b64_e32 v[26:27], 0
	v_mov_b64_e32 v[28:29], 0
	v_mov_b64_e32 v[30:31], 0
	v_mov_b64_e32 v[32:33], 0
	v_mov_b64_e32 v[34:35], 0
	v_mov_b64_e32 v[36:37], 0
	v_mov_b64_e32 v[38:39], 0
	v_mov_b64_e32 v[40:41], 0
	v_mov_b64_e32 v[42:43], 0
	v_mov_b64_e32 v[44:45], 0
	v_mov_b64_e32 v[46:47], 0
	v_mov_b64_e32 v[48:49], 0
	v_mov_b64_e32 v[50:51], 0
	v_mov_b64_e32 v[52:53], 0
	v_mov_b64_e32 v[54:55], 0
	v_mov_b64_e32 v[56:57], 0
	v_mov_b64_e32 v[58:59], 0
	v_mov_b64_e32 v[60:61], 0
	v_mov_b64_e32 v[62:63], 0
	v_mov_b64_e32 v[64:65], 0
	v_mov_b64_e32 v[66:67], 0
	v_mov_b64_e32 v[68:69], 0
	v_mov_b64_e32 v[70:71], 0
	v_mov_b64_e32 v[72:73], 0
	v_mov_b64_e32 v[74:75], 0
	v_mov_b64_e32 v[76:77], 0
	v_mov_b64_e32 v[78:79], 0
	v_mov_b64_e32 v[80:81], 0
	v_mov_b64_e32 v[82:83], 0
	v_mov_b64_e32 v[84:85], 0
	v_mov_b64_e32 v[86:87], 0
	v_mov_b64_e32 v[88:89], 0
	v_mov_b64_e32 v[90:91], 0
	v_mov_b64_e32 v[92:93], 0
	v_mov_b64_e32 v[94:95], 0
	v_mov_b64_e32 v[96:97], 0
	v_mov_b64_e32 v[102:103], 0
	v_mov_b64_e32 v[104:105], 0
	v_mov_b64_e32 v[110:111], 0
	v_mov_b64_e32 v[112:113], 0
	v_mov_b64_e32 v[118:119], 0
	v_mov_b64_e32 v[120:121], 0
	v_mov_b64_e32 v[126:127], 0
	v_mov_b64_e32 v[128:129], 0
	v_mov_b64_e32 v[130:131], 0
	v_mov_b64_e32 v[132:133], 0
	v_mov_b64_e32 v[134:135], 0
	v_mov_b64_e32 v[136:137], 0
	v_mov_b64_e32 v[138:139], 0
	v_mov_b64_e32 v[140:141], 0
	v_mov_b64_e32 v[142:143], 0
	v_mov_b64_e32 v[144:145], 0
	v_mov_b32_e32 v3, 0

.LBB0_532:
	s_ashr_i32 s13, s12, 31
	s_lshl_b64 s[14:15], s[12:13], 19
	s_add_u32 s14, s27, s14
	s_addc_u32 s15, s28, s15
	s_ashr_i32 s11, s10, 31
	s_lshl_b64 s[16:17], s[10:11], 19
	s_add_u32 s16, s29, s16
	v_mov_b32_e32 v145, 0
	s_addc_u32 s17, s30, s17
	s_andn2_b64 vcc, exec, s[6:7]
	s_waitcnt vmcnt(0)
	s_cbranch_vccnz .Lzt_14
	v_mov_b64_e32 v[2:3], 0x180
	v_cmp_lt_i64_e32 vcc, s[24:25], v[2:3]
	s_and_b64 s[24:25], vcc, exec
	s_cselect_b32 s11, s15, s21
	s_cselect_b32 s13, s14, s20
	s_cselect_b32 s19, s17, s23
	s_cselect_b32 s38, s16, s22
	s_add_u32 s20, s20, 0x40080
	s_addc_u32 s21, s21, 0
	s_add_u32 s39, s22, 0x100
	v_mov_b32_e32 v2, 0
	s_addc_u32 s56, s23, 0
	s_mov_b32 s22, 0
	v_mov_b64_e32 v[4:5], 0
	v_mov_b64_e32 v[6:7], 0
	v_mov_b64_e32 v[8:9], 0
	v_mov_b64_e32 v[10:11], 0
	v_mov_b64_e32 v[12:13], 0
	v_mov_b64_e32 v[14:15], 0
	v_mov_b64_e32 v[16:17], 0
	v_mov_b64_e32 v[18:19], 0
	v_mov_b64_e32 v[20:21], 0
	v_mov_b64_e32 v[22:23], 0
	v_mov_b64_e32 v[24:25], 0
	v_mov_b64_e32 v[26:27], 0
	v_mov_b64_e32 v[28:29], 0
	v_mov_b64_e32 v[30:31], 0
	v_mov_b64_e32 v[32:33], 0
	v_mov_b64_e32 v[42:43], 0
	v_mov_b64_e32 v[44:45], 0
	v_mov_b64_e32 v[46:47], 0
	v_mov_b64_e32 v[48:49], 0
	v_mov_b64_e32 v[50:51], 0
	v_mov_b64_e32 v[52:53], 0
	v_mov_b64_e32 v[54:55], 0
	v_mov_b64_e32 v[56:57], 0
	v_mov_b64_e32 v[66:67], 0
	v_mov_b64_e32 v[68:69], 0
	v_mov_b64_e32 v[70:71], 0
	v_mov_b64_e32 v[72:73], 0
	v_mov_b64_e32 v[74:75], 0
	v_mov_b64_e32 v[76:77], 0
	v_mov_b64_e32 v[78:79], 0
	v_mov_b64_e32 v[80:81], 0
	v_mov_b64_e32 v[82:83], 0
	v_mov_b64_e32 v[84:85], 0
	v_mov_b64_e32 v[86:87], 0
	v_mov_b64_e32 v[88:89], 0
	v_mov_b64_e32 v[90:91], 0
	v_mov_b64_e32 v[92:93], 0
	v_mov_b64_e32 v[94:95], 0
	v_mov_b64_e32 v[96:97], 0
	v_mov_b64_e32 v[98:99], 0
	v_mov_b64_e32 v[100:101], 0
	v_mov_b64_e32 v[102:103], 0
	v_mov_b64_e32 v[104:105], 0
	v_mov_b64_e32 v[106:107], 0
	v_mov_b64_e32 v[108:109], 0
	v_mov_b64_e32 v[110:111], 0
	v_mov_b64_e32 v[112:113], 0
	v_mov_b64_e32 v[114:115], 0
	v_mov_b64_e32 v[116:117], 0
	v_mov_b64_e32 v[118:119], 0
	v_mov_b64_e32 v[120:121], 0
	v_mov_b64_e32 v[122:123], 0
	v_mov_b64_e32 v[124:125], 0
	v_mov_b64_e32 v[126:127], 0
	v_mov_b64_e32 v[128:129], 0
	v_mov_b64_e32 v[130:131], 0
	v_mov_b64_e32 v[132:133], 0
	v_mov_b64_e32 v[134:135], 0
	v_mov_b64_e32 v[136:137], 0
	v_mov_b64_e32 v[138:139], 0
	v_mov_b64_e32 v[140:141], 0
	v_mov_b64_e32 v[142:143], 0
	v_mov_b64_e32 v[144:145], 0
	v_mov_b32_e32 v3, 0

.LBB0_590:
	v_mov_b32_e32 v141, 0
	s_andn2_b64 vcc, exec, s[8:9]
	s_waitcnt vmcnt(0)
	s_waitcnt lgkmcnt(0)
	s_cbranch_vccnz .Lzt_18
	s_add_u32 s49, s10, 0x100
	s_addc_u32 s50, s11, 0
	s_add_u32 s10, s12, 0xc000
	v_mov_b32_e32 v2, 0
	s_addc_u32 s11, s13, 0
	s_mov_b32 s12, 0
	v_mov_b64_e32 v[4:5], 0
	v_mov_b64_e32 v[6:7], 0
	v_mov_b64_e32 v[8:9], 0
	v_mov_b64_e32 v[10:11], 0
	v_mov_b64_e32 v[12:13], 0
	v_mov_b64_e32 v[14:15], 0
	v_mov_b64_e32 v[16:17], 0
	v_mov_b64_e32 v[18:19], 0
	v_mov_b64_e32 v[20:21], 0
	v_mov_b64_e32 v[22:23], 0
	v_mov_b64_e32 v[24:25], 0
	v_mov_b64_e32 v[26:27], 0
	v_mov_b64_e32 v[28:29], 0
	v_mov_b64_e32 v[30:31], 0
	v_mov_b64_e32 v[32:33], 0
	v_mov_b64_e32 v[34:35], 0
	v_mov_b64_e32 v[36:37], 0
	v_mov_b64_e32 v[38:39], 0
	v_mov_b64_e32 v[40:41], 0
	v_mov_b64_e32 v[42:43], 0
	v_mov_b64_e32 v[44:45], 0
	v_mov_b64_e32 v[46:47], 0
	v_mov_b64_e32 v[48:49], 0
	v_mov_b64_e32 v[50:51], 0
	v_mov_b64_e32 v[52:53], 0
	v_mov_b64_e32 v[54:55], 0
	v_mov_b64_e32 v[56:57], 0
	v_mov_b64_e32 v[58:59], 0
	v_mov_b64_e32 v[60:61], 0
	v_mov_b64_e32 v[62:63], 0
	v_mov_b64_e32 v[64:65], 0
	v_mov_b64_e32 v[74:75], 0
	v_mov_b64_e32 v[76:77], 0
	v_mov_b64_e32 v[78:79], 0
	v_mov_b64_e32 v[80:81], 0
	v_mov_b64_e32 v[82:83], 0
	v_mov_b64_e32 v[84:85], 0
	v_mov_b64_e32 v[86:87], 0
	v_mov_b64_e32 v[88:89], 0
	v_mov_b64_e32 v[98:99], 0
	v_mov_b64_e32 v[100:101], 0
	v_mov_b64_e32 v[102:103], 0
	v_mov_b64_e32 v[104:105], 0
	v_mov_b64_e32 v[106:107], 0
	v_mov_b64_e32 v[108:109], 0
	v_mov_b64_e32 v[110:111], 0
	v_mov_b64_e32 v[112:113], 0
	v_mov_b64_e32 v[114:115], 0
	v_mov_b64_e32 v[116:117], 0
	v_mov_b64_e32 v[118:119], 0
	v_mov_b64_e32 v[120:121], 0
	v_mov_b64_e32 v[122:123], 0
	v_mov_b64_e32 v[124:125], 0
	v_mov_b64_e32 v[126:127], 0
	v_mov_b64_e32 v[128:129], 0
	v_mov_b64_e32 v[130:131], 0
	v_mov_b64_e32 v[132:133], 0
	v_mov_b64_e32 v[134:135], 0
	v_mov_b64_e32 v[136:137], 0
	v_mov_b64_e32 v[138:139], 0
	v_mov_b64_e32 v[140:141], 0
	v_mov_b64_e32 v[142:143], 0
	v_mov_b64_e32 v[144:145], 0
	v_mov_b32_e32 v3, 0

.LBB0_797:
	s_ashr_i32 s15, s14, 31
	s_lshl_b64 s[16:17], s[14:15], 19
	s_add_u32 s16, s64, s16
	s_addc_u32 s17, s65, s17
	s_ashr_i32 s13, s12, 31
	s_lshl_b64 s[18:19], s[12:13], 19
	s_add_u32 s18, s31, s18
	v_mov_b32_e32 v145, 0
	s_addc_u32 s19, s34, s19
	s_andn2_b64 vcc, exec, s[8:9]
	s_waitcnt vmcnt(0)
	s_cbranch_vccnz .Lzt_24
	v_mov_b64_e32 v[2:3], 0x600
	v_cmp_lt_i64_e32 vcc, s[28:29], v[2:3]
	s_and_b64 s[28:29], vcc, exec
	s_cselect_b32 s13, s17, s25
	s_cselect_b32 s15, s16, s24
	s_cselect_b32 s21, s19, s27
	s_cselect_b32 s39, s18, s26
	s_add_u32 s24, s24, 0x40080
	s_addc_u32 s25, s25, 0
	s_add_u32 s55, s26, 0x100
	v_mov_b32_e32 v2, 0
	s_addc_u32 s56, s27, 0
	s_mov_b32 s26, 0
	v_mov_b64_e32 v[4:5], 0
	v_mov_b64_e32 v[6:7], 0
	v_mov_b64_e32 v[8:9], 0
	v_mov_b64_e32 v[10:11], 0
	v_mov_b64_e32 v[12:13], 0
	v_mov_b64_e32 v[14:15], 0
	v_mov_b64_e32 v[16:17], 0
	v_mov_b64_e32 v[18:19], 0
	v_mov_b64_e32 v[20:21], 0
	v_mov_b64_e32 v[26:27], 0
	v_mov_b64_e32 v[28:29], 0
	v_mov_b64_e32 v[30:31], 0
	v_mov_b64_e32 v[32:33], 0
	v_mov_b64_e32 v[38:39], 0
	v_mov_b64_e32 v[40:41], 0
	v_mov_b64_e32 v[50:51], 0
	v_mov_b64_e32 v[52:53], 0
	v_mov_b64_e32 v[54:55], 0
	v_mov_b64_e32 v[56:57], 0
	v_mov_b64_e32 v[58:59], 0
	v_mov_b64_e32 v[60:61], 0
	v_mov_b64_e32 v[62:63], 0
	v_mov_b64_e32 v[64:65], 0
	v_mov_b64_e32 v[66:67], 0
	v_mov_b64_e32 v[68:69], 0
	v_mov_b64_e32 v[70:71], 0
	v_mov_b64_e32 v[72:73], 0
	v_mov_b64_e32 v[74:75], 0
	v_mov_b64_e32 v[76:77], 0
	v_mov_b64_e32 v[78:79], 0
	v_mov_b64_e32 v[80:81], 0
	v_mov_b64_e32 v[82:83], 0
	v_mov_b64_e32 v[84:85], 0
	v_mov_b64_e32 v[86:87], 0
	v_mov_b64_e32 v[88:89], 0
	v_mov_b64_e32 v[90:91], 0
	v_mov_b64_e32 v[92:93], 0
	v_mov_b64_e32 v[94:95], 0
	v_mov_b64_e32 v[96:97], 0
	v_mov_b64_e32 v[98:99], 0
	v_mov_b64_e32 v[100:101], 0
	v_mov_b64_e32 v[102:103], 0
	v_mov_b64_e32 v[104:105], 0
	v_mov_b64_e32 v[106:107], 0
	v_mov_b64_e32 v[108:109], 0
	v_mov_b64_e32 v[110:111], 0
	v_mov_b64_e32 v[112:113], 0
	v_mov_b64_e32 v[114:115], 0
	v_mov_b64_e32 v[116:117], 0
	v_mov_b64_e32 v[118:119], 0
	v_mov_b64_e32 v[120:121], 0
	v_mov_b64_e32 v[122:123], 0
	v_mov_b64_e32 v[124:125], 0
	v_mov_b64_e32 v[126:127], 0
	v_mov_b64_e32 v[128:129], 0
	v_mov_b64_e32 v[130:131], 0
	v_mov_b64_e32 v[132:133], 0
	v_mov_b64_e32 v[134:135], 0
	v_mov_b64_e32 v[136:137], 0
	v_mov_b64_e32 v[138:139], 0
	v_mov_b64_e32 v[140:141], 0
	v_mov_b64_e32 v[142:143], 0
	v_mov_b64_e32 v[144:145], 0
	v_mov_b32_e32 v3, 0

.LBB0_842:
	v_mov_b32_e32 v137, 0
	s_andn2_b64 vcc, exec, s[10:11]
	s_waitcnt vmcnt(0)
	s_waitcnt lgkmcnt(0)
	s_cbranch_vccnz .Lzt_26
	s_add_u32 s51, s12, 0x100
	s_addc_u32 s52, s13, 0
	s_add_u32 s12, s14, 0xc000
	v_mov_b32_e32 v2, 0
	s_addc_u32 s13, s15, 0
	s_mov_b32 s14, 0
	v_mov_b64_e32 v[4:5], 0
	v_mov_b64_e32 v[6:7], 0
	v_mov_b64_e32 v[8:9], 0
	v_mov_b64_e32 v[10:11], 0
	v_mov_b64_e32 v[12:13], 0
	v_mov_b64_e32 v[14:15], 0
	v_mov_b64_e32 v[16:17], 0
	v_mov_b64_e32 v[18:19], 0
	v_mov_b64_e32 v[20:21], 0
	v_mov_b64_e32 v[22:23], 0
	v_mov_b64_e32 v[24:25], 0
	v_mov_b64_e32 v[26:27], 0
	v_mov_b64_e32 v[28:29], 0
	v_mov_b64_e32 v[30:31], 0
	v_mov_b64_e32 v[32:33], 0
	v_mov_b64_e32 v[34:35], 0
	v_mov_b64_e32 v[36:37], 0
	v_mov_b64_e32 v[38:39], 0
	v_mov_b64_e32 v[40:41], 0
	v_mov_b64_e32 v[42:43], 0
	v_mov_b64_e32 v[44:45], 0
	v_mov_b64_e32 v[46:47], 0
	v_mov_b64_e32 v[48:49], 0
	v_mov_b64_e32 v[50:51], 0
	v_mov_b64_e32 v[52:53], 0
	v_mov_b64_e32 v[54:55], 0
	v_mov_b64_e32 v[56:57], 0
	v_mov_b64_e32 v[58:59], 0
	v_mov_b64_e32 v[60:61], 0
	v_mov_b64_e32 v[62:63], 0
	v_mov_b64_e32 v[64:65], 0
	v_mov_b64_e32 v[66:67], 0
	v_mov_b64_e32 v[68:69], 0
	v_mov_b64_e32 v[70:71], 0
	v_mov_b64_e32 v[72:73], 0
	v_mov_b64_e32 v[74:75], 0
	v_mov_b64_e32 v[76:77], 0
	v_mov_b64_e32 v[78:79], 0
	v_mov_b64_e32 v[80:81], 0
	v_mov_b64_e32 v[82:83], 0
	v_mov_b64_e32 v[84:85], 0
	v_mov_b64_e32 v[86:87], 0
	v_mov_b64_e32 v[88:89], 0
	v_mov_b64_e32 v[90:91], 0
	v_mov_b64_e32 v[92:93], 0
	v_mov_b64_e32 v[94:95], 0
	v_mov_b64_e32 v[96:97], 0
	v_mov_b64_e32 v[98:99], 0
	v_mov_b64_e32 v[100:101], 0
	v_mov_b64_e32 v[102:103], 0
	v_mov_b64_e32 v[104:105], 0
	v_mov_b64_e32 v[106:107], 0
	v_mov_b64_e32 v[108:109], 0
	v_mov_b64_e32 v[110:111], 0
	v_mov_b64_e32 v[112:113], 0
	v_mov_b64_e32 v[114:115], 0
	v_mov_b64_e32 v[116:117], 0
	v_mov_b64_e32 v[118:119], 0
	v_mov_b64_e32 v[120:121], 0
	v_mov_b64_e32 v[122:123], 0
	v_mov_b64_e32 v[124:125], 0
	v_mov_b64_e32 v[134:135], 0
	v_mov_b64_e32 v[136:137], 0
	v_mov_b32_e32 v3, 0

.LBB0_872:
	s_ashr_i32 s5, s4, 31
	s_lshl_b64 s[6:7], s[4:5], 19
	s_add_u32 s6, s64, s6
	s_addc_u32 s7, s65, s7
	s_ashr_i32 s3, s2, 31
	s_lshl_b64 s[8:9], s[2:3], 19
	s_add_u32 s8, s66, s8
	v_mov_b32_e32 v141, 0
	s_addc_u32 s9, s67, s9
	s_andn2_b64 vcc, exec, s[0:1]
	s_waitcnt vmcnt(0)
	s_cbranch_vccnz .Lzt_28
	v_mov_b64_e32 v[2:3], 0xb00
	v_cmp_lt_i64_e32 vcc, s[16:17], v[2:3]
	s_and_b64 s[16:17], vcc, exec
	s_cselect_b32 s3, s7, s13
	s_cselect_b32 s5, s6, s12
	s_cselect_b32 s39, s9, s15
	s_cselect_b32 s40, s8, s14
	s_add_u32 s12, s12, 0x40080
	s_addc_u32 s13, s13, 0
	s_add_u32 s41, s14, 0x100
	v_mov_b32_e32 v2, 0
	s_addc_u32 s42, s15, 0
	s_mov_b32 s14, 0
	v_mov_b64_e32 v[4:5], 0
	v_mov_b64_e32 v[6:7], 0
	v_mov_b64_e32 v[8:9], 0
	v_mov_b64_e32 v[10:11], 0
	v_mov_b64_e32 v[12:13], 0
	v_mov_b64_e32 v[14:15], 0
	v_mov_b64_e32 v[16:17], 0
	v_mov_b64_e32 v[18:19], 0
	v_mov_b64_e32 v[20:21], 0
	v_mov_b64_e32 v[22:23], 0
	v_mov_b64_e32 v[24:25], 0
	v_mov_b64_e32 v[26:27], 0
	v_mov_b64_e32 v[28:29], 0
	v_mov_b64_e32 v[30:31], 0
	v_mov_b64_e32 v[32:33], 0
	v_mov_b64_e32 v[34:35], 0
	v_mov_b64_e32 v[36:37], 0
	v_mov_b64_e32 v[38:39], 0
	v_mov_b64_e32 v[40:41], 0
	v_mov_b64_e32 v[42:43], 0
	v_mov_b64_e32 v[44:45], 0
	v_mov_b64_e32 v[46:47], 0
	v_mov_b64_e32 v[48:49], 0
	v_mov_b64_e32 v[50:51], 0
	v_mov_b64_e32 v[52:53], 0
	v_mov_b64_e32 v[54:55], 0
	v_mov_b64_e32 v[56:57], 0
	v_mov_b64_e32 v[58:59], 0
	v_mov_b64_e32 v[60:61], 0
	v_mov_b64_e32 v[62:63], 0
	v_mov_b64_e32 v[64:65], 0
	v_mov_b64_e32 v[66:67], 0
	v_mov_b64_e32 v[68:69], 0
	v_mov_b64_e32 v[70:71], 0
	v_mov_b64_e32 v[72:73], 0
	v_mov_b64_e32 v[74:75], 0
	v_mov_b64_e32 v[76:77], 0
	v_mov_b64_e32 v[78:79], 0
	v_mov_b64_e32 v[80:81], 0
	v_mov_b64_e32 v[90:91], 0
	v_mov_b64_e32 v[92:93], 0
	v_mov_b64_e32 v[94:95], 0
	v_mov_b64_e32 v[96:97], 0
	v_mov_b64_e32 v[106:107], 0
	v_mov_b64_e32 v[108:109], 0
	v_mov_b64_e32 v[110:111], 0
	v_mov_b64_e32 v[112:113], 0
	v_mov_b64_e32 v[114:115], 0
	v_mov_b64_e32 v[116:117], 0
	v_mov_b64_e32 v[118:119], 0
	v_mov_b64_e32 v[120:121], 0
	v_mov_b64_e32 v[122:123], 0
	v_mov_b64_e32 v[124:125], 0
	v_mov_b64_e32 v[126:127], 0
	v_mov_b64_e32 v[128:129], 0
	v_mov_b64_e32 v[130:131], 0
	v_mov_b64_e32 v[132:133], 0
	v_mov_b64_e32 v[134:135], 0
	v_mov_b64_e32 v[136:137], 0
	v_mov_b64_e32 v[138:139], 0
	v_mov_b64_e32 v[140:141], 0
	v_mov_b64_e32 v[142:143], 0
	v_mov_b64_e32 v[144:145], 0
	v_mov_b32_e32 v3, 0
